# gate/up unit loop: wait only for the LDS-DMA loads (vmcnt(8)) instead of draining the previous unit's 8 epilogue stores before the next K loop
# speedup vs baseline: 1.0047x; 1.0047x over previous
; DI int tidx() { int t = threadIdx.x; asm volatile("" : "+v"(t)); return t; }
; #define PG8_STAGE(bufoff, gbase, voff) do { _Pragma("unroll") for (int _i = 0; _i < 2; ++_i) \
;     __builtin_amdgcn_global_load_lds((const unsigned*)((const char*)(gbase) + (voff)[_i]), (LAS unsigned*)(lds + (bufoff) + ldsw + _i * 8192), 16, 0, 0); } while (0)
; #define PG8_WAIT_V(n) asm volatile("s_waitcnt vmcnt(" #n ")" ::: "memory")
; #define PG8_BAR __builtin_amdgcn_s_barrier()
; template <class Epi, class Sched>
; DI void gemm_phase(LAS unsigned char* lds, const Gemm g, const Sched& S, const Epi& E) {
;   const int tid = tidx(), wid = __builtin_amdgcn_readfirstlane(tid >> 6), lane = tid & 63, wr = wid >> 2, wc = wid & 3, fr = lane & 15, fq = lane >> 4;
;   int K = g.K; asm volatile("" : "+s"(K));
;   const int nt = K / BK;
;   unsigned voffA[2], voffB[2];
; #pragma unroll
;   for (int i = 0; i < 2; ++i) {
;     int R, C; stage_rc(tid * 16 + i * 8192, R, C);
;     int Rb = R;
;     if (Epi::BMAP == 1) Rb = (R & ~31) + perm32(R & 31);
;     if (Epi::BMAP == 2) Rb = 64 * (R >> 5) + perm32(R & 31);
;     voffA[i] = (unsigned)(R * K + C) * 2u; voffB[i] = (unsigned)(Rb * K + C) * 2u;
;   }
;   const size_t kstep = (size_t)(BK * 2);
;   const size_t hstep = (size_t)HALF * K * 2;
;   const size_t hstepB = (Epi::BMAP == 2) ? (size_t)32 * K * 2 : hstep;
;   const size_t tstep = 2 * hstep;
;   const unsigned ldsw = (unsigned)wid * 1024u;
;   const int aoff = lds_byte(wr * 64 + fr, fq * 8), boff = lds_byte(wc * 32 + fr, fq * 8);
;     ...
;   PG8_WAIT_V(4); PG8_BAR;
;   PG8_STAGE(PG8_SB(1, 0), cB + kstep, voffB); PG8_STAGE(PG8_SA(1, 0), cA + kstep, voffA); PG8_STAGE(PG8_SB(1, 1), cB + hstepB + kstep, voffB);
;   PG8_WAIT_V(6); PG8_BAR;
.LBB0_160:
	s_add_i32 m0, s36, 0x18000
	v_lshl_add_u64 v[2:3], v[2:3], 0, s[70:71]
	s_waitcnt vmcnt(4)
	s_barrier
	global_load_lds_dwordx4 v[2:3], off
	v_lshl_add_u64 v[2:3], v[4:5], 0, s[70:71]
	s_add_i32 m0, s36, 0x1a000
	s_add_i32 s41, s36, 0x8000
	global_load_lds_dwordx4 v[2:3], off
	v_lshl_add_u64 v[2:3], v[6:7], 0, s[70:71]
	s_mov_b32 m0, s41
	s_add_i32 s42, s36, 0xa000
	global_load_lds_dwordx4 v[2:3], off
	v_lshl_add_u64 v[2:3], v[8:9], 0, s[70:71]
	s_mov_b32 m0, s42
	v_lshrrev_b32_e32 v22, 1, v20
	global_load_lds_dwordx4 v[2:3], off
	s_add_i32 m0, s36, 0x1c000
	v_lshl_add_u64 v[2:3], v[10:11], 0, s[70:71]
	global_load_lds_dwordx4 v[2:3], off
	v_lshl_add_u64 v[2:3], v[12:13], 0, s[70:71]
	s_add_i32 m0, s36, 0x1e000
	s_lshr_b32 s3, s3, 26
	global_load_lds_dwordx4 v[2:3], off
	v_and_b32_e32 v22, 24, v22
	v_and_b32_e32 v21, 15, v20
	s_add_i32 s3, s2, s3
	v_lshlrev_b32_e32 v23, 1, v22
	v_lshlrev_b32_e32 v20, 2, v20
	s_ashr_i32 s40, s3, 6
	v_lshl_or_b32 v140, s17, 6, v21
	v_lshl_or_b32 v21, v21, 6, v23
	s_lshl_b32 s3, s17, 13
	v_and_b32_e32 v20, 32, v20
	v_readlane_b32 s14, v252, 47
	v_readlane_b32 s18, v254, 35
	v_bitop3_b32 v23, v21, s3, v20 bitop3:0xde
	s_lshl_b32 s3, s16, 5
	v_add_u32_e32 v2, v19, v17
	v_readlane_b32 s15, v252, 48
	v_readlane_b32 s19, v254, 36
	s_and_b32 s3, s3, 0x60
	v_add_lshl_u32 v2, v2, v18, 1
	v_mov_b32_e32 v3, v1
	s_nor_b64 s[14:15], s[14:15], s[18:19]
	s_lshl_b32 s16, s3, 7
	s_waitcnt vmcnt(6)
	v_lshl_add_u64 v[136:137], s[0:1], 0, v[2:3]
	v_add_u32_e32 v2, v16, v14
	s_cmp_gt_i32 s2, 63
	v_add_lshl_u32 v2, v2, v15, 1
	v_bitop3_b32 v141, v21, s16, v20 bitop3:0xde
	s_cselect_b64 s[16:17], -1, 0
	s_add_i32 s43, s40, -2
	v_or_b32_e32 v142, s3, v22
	v_lshl_add_u64 v[138:139], s[0:1], 0, v[2:3]
	s_mov_b32 s49, 0
	v_add_u32_e32 v143, 16, v23
	v_readlane_b32 s47, v252, 51
	v_readlane_b32 s48, v252, 52
	s_waitcnt vmcnt(0)
	s_barrier
	s_branch .LBB0_163

; template <class Epi, class Sched>
; DI void gemm_phase(LAS unsigned char* lds, const Gemm g, const Sched& S, const Epi& E) {
;     ...
;     if (!has_next) break;
; #pragma unroll
;     for (int a = 0; a < 2; ++a)
; #pragma unroll
;       for (int b = 0; b < 2; ++b)
; #pragma unroll
;         for (int m = 0; m < 4; ++m)
; #pragma unroll
;           for (int n = 0; n < 2; ++n) acc[a][b][m][n] = (f32x4){0.f, 0.f, 0.f, 0.f};
;     cur = nxt; cA = nA; cB = nB; ++ui;
.LBB0_176:
	s_waitcnt vmcnt(8)
	v_mov_b32_e32 v125, 0
	s_andn2_b64 vcc, exec, s[16:17]
	v_mov_b32_e32 v124, v125
	v_mov_b32_e32 v123, v125
	v_mov_b32_e32 v122, v125
	v_mov_b32_e32 v121, v125
	v_mov_b32_e32 v120, v125
	v_mov_b32_e32 v119, v125
	v_mov_b32_e32 v118, v125
	v_mov_b32_e32 v113, v125
	v_mov_b32_e32 v112, v125
	v_mov_b32_e32 v111, v125
	v_mov_b32_e32 v110, v125
	v_mov_b32_e32 v105, v125
	v_mov_b32_e32 v104, v125
	v_mov_b32_e32 v103, v125
	v_mov_b32_e32 v102, v125
	v_mov_b32_e32 v97, v125
	v_mov_b32_e32 v96, v125
	v_mov_b32_e32 v95, v125
	v_mov_b32_e32 v94, v125
	v_mov_b32_e32 v89, v125
	v_mov_b32_e32 v88, v125
	v_mov_b32_e32 v87, v125
	v_mov_b32_e32 v86, v125
	v_mov_b32_e32 v81, v125
	v_mov_b32_e32 v80, v125
	v_mov_b32_e32 v79, v125
	v_mov_b32_e32 v78, v125
	v_mov_b32_e32 v73, v125
	v_mov_b32_e32 v72, v125
	v_mov_b32_e32 v71, v125
	v_mov_b32_e32 v70, v125
	v_mov_b32_e32 v129, v125
	v_mov_b32_e32 v128, v125
	v_mov_b32_e32 v127, v125
	v_mov_b32_e32 v126, v125
	v_mov_b32_e32 v117, v125
	v_mov_b32_e32 v116, v125
	v_mov_b32_e32 v115, v125
	v_mov_b32_e32 v114, v125
	v_mov_b32_e32 v109, v125
	v_mov_b32_e32 v108, v125
	v_mov_b32_e32 v107, v125
	v_mov_b32_e32 v106, v125
	v_mov_b32_e32 v101, v125
	v_mov_b32_e32 v100, v125
	v_mov_b32_e32 v99, v125
	v_mov_b32_e32 v98, v125
	v_mov_b32_e32 v93, v125
	v_mov_b32_e32 v92, v125
	v_mov_b32_e32 v91, v125
	v_mov_b32_e32 v90, v125
	v_mov_b32_e32 v85, v125
	v_mov_b32_e32 v84, v125
	v_mov_b32_e32 v83, v125
	v_mov_b32_e32 v82, v125
	v_mov_b32_e32 v77, v125
	v_mov_b32_e32 v76, v125
	v_mov_b32_e32 v75, v125
	v_mov_b32_e32 v74, v125
	v_mov_b32_e32 v69, v125
	v_mov_b32_e32 v68, v125
	v_mov_b32_e32 v67, v125
	v_mov_b32_e32 v66, v125
	v_mov_b32_e32 v65, v125
	v_mov_b32_e32 v64, v125
	v_mov_b32_e32 v63, v125
	v_mov_b32_e32 v62, v125
	v_mov_b32_e32 v57, v125
	v_mov_b32_e32 v56, v125
	v_mov_b32_e32 v55, v125
	v_mov_b32_e32 v54, v125
	v_mov_b32_e32 v49, v125
	v_mov_b32_e32 v48, v125
	v_mov_b32_e32 v47, v125
	v_mov_b32_e32 v46, v125
	v_mov_b32_e32 v41, v125
	v_mov_b32_e32 v40, v125
	v_mov_b32_e32 v39, v125
	v_mov_b32_e32 v38, v125
	v_mov_b32_e32 v33, v125
	v_mov_b32_e32 v32, v125
	v_mov_b32_e32 v31, v125
	v_mov_b32_e32 v30, v125
	v_mov_b32_e32 v25, v125
	v_mov_b32_e32 v24, v125
	v_mov_b32_e32 v23, v125
	v_mov_b32_e32 v22, v125
	v_mov_b32_e32 v17, v125
	v_mov_b32_e32 v16, v125
	v_mov_b32_e32 v15, v125
	v_mov_b32_e32 v14, v125
	v_mov_b32_e32 v9, v125
	v_mov_b32_e32 v8, v125
	v_mov_b32_e32 v7, v125
	v_mov_b32_e32 v6, v125
	v_mov_b32_e32 v61, v125
	v_mov_b32_e32 v60, v125
	v_mov_b32_e32 v59, v125
	v_mov_b32_e32 v58, v125
	v_mov_b32_e32 v53, v125
	v_mov_b32_e32 v52, v125
	v_mov_b32_e32 v51, v125
	v_mov_b32_e32 v50, v125
	v_mov_b32_e32 v45, v125
	v_mov_b32_e32 v44, v125
	v_mov_b32_e32 v43, v125
	v_mov_b32_e32 v42, v125
	v_mov_b32_e32 v37, v125
	v_mov_b32_e32 v36, v125
	v_mov_b32_e32 v35, v125
	v_mov_b32_e32 v34, v125
	v_mov_b32_e32 v29, v125
	v_mov_b32_e32 v28, v125
	v_mov_b32_e32 v27, v125
	v_mov_b32_e32 v26, v125
	v_mov_b32_e32 v21, v125
	v_mov_b32_e32 v20, v125
	v_mov_b32_e32 v19, v125
	v_mov_b32_e32 v18, v125
	v_mov_b32_e32 v13, v125
	v_mov_b32_e32 v12, v125
	v_mov_b32_e32 v11, v125
	v_mov_b32_e32 v10, v125
	v_mov_b32_e32 v5, v125
	v_mov_b32_e32 v4, v125
	v_mov_b32_e32 v3, v125
	v_mov_b32_e32 v2, v125
	s_cbranch_vccnz .LBB0_162
	s_add_u32 s22, s22, 0x80
	s_addc_u32 s23, s23, 0
	s_add_u32 s49, s24, 0x100
	v_mov_b32_e32 v2, 0
	s_addc_u32 s50, s25, 0
	s_mov_b32 s24, 0
	v_mov_b32_e32 v3, v2
	v_mov_b32_e32 v4, v2
	v_mov_b32_e32 v5, v2
	v_mov_b32_e32 v10, v2
	v_mov_b32_e32 v11, v2
	v_mov_b32_e32 v12, v2
	v_mov_b32_e32 v13, v2
	v_mov_b32_e32 v18, v2
	v_mov_b32_e32 v19, v2
	v_mov_b32_e32 v20, v2
	v_mov_b32_e32 v21, v2
	v_mov_b32_e32 v26, v2
	v_mov_b32_e32 v27, v2
	v_mov_b32_e32 v28, v2
	v_mov_b32_e32 v29, v2
	v_mov_b32_e32 v34, v2
	v_mov_b32_e32 v35, v2
	v_mov_b32_e32 v36, v2
	v_mov_b32_e32 v37, v2
	v_mov_b32_e32 v42, v2
	v_mov_b32_e32 v43, v2
	v_mov_b32_e32 v44, v2
	v_mov_b32_e32 v45, v2
	v_mov_b32_e32 v50, v2
	v_mov_b32_e32 v51, v2
	v_mov_b32_e32 v52, v2
	v_mov_b32_e32 v53, v2
	v_mov_b32_e32 v58, v2
	v_mov_b32_e32 v59, v2
	v_mov_b32_e32 v60, v2
	v_mov_b32_e32 v61, v2
	v_mov_b32_e32 v6, v2
	v_mov_b32_e32 v7, v2
	v_mov_b32_e32 v8, v2
	v_mov_b32_e32 v9, v2
	v_mov_b32_e32 v14, v2
	v_mov_b32_e32 v15, v2
	v_mov_b32_e32 v16, v2
	v_mov_b32_e32 v17, v2
	v_mov_b32_e32 v22, v2
	v_mov_b32_e32 v23, v2
	v_mov_b32_e32 v24, v2
	v_mov_b32_e32 v25, v2
	v_mov_b32_e32 v30, v2
	v_mov_b32_e32 v31, v2
	v_mov_b32_e32 v32, v2
	v_mov_b32_e32 v33, v2
	v_mov_b32_e32 v38, v2
	v_mov_b32_e32 v39, v2
	v_mov_b32_e32 v40, v2
	v_mov_b32_e32 v41, v2
	v_mov_b32_e32 v46, v2
	v_mov_b32_e32 v47, v2
	v_mov_b32_e32 v48, v2
	v_mov_b32_e32 v49, v2
	v_mov_b32_e32 v54, v2
	v_mov_b32_e32 v55, v2
	v_mov_b32_e32 v56, v2
	v_mov_b32_e32 v57, v2
	v_mov_b32_e32 v62, v2
	v_mov_b32_e32 v63, v2
	v_mov_b32_e32 v64, v2
	v_mov_b32_e32 v65, v2
	v_mov_b32_e32 v66, v2
	v_mov_b32_e32 v67, v2
	v_mov_b32_e32 v68, v2
	v_mov_b32_e32 v69, v2
	v_mov_b32_e32 v74, v2
	v_mov_b32_e32 v75, v2
	v_mov_b32_e32 v76, v2
	v_mov_b32_e32 v77, v2
	v_mov_b32_e32 v82, v2
	v_mov_b32_e32 v83, v2
	v_mov_b32_e32 v84, v2
	v_mov_b32_e32 v85, v2
	v_mov_b32_e32 v90, v2
	v_mov_b32_e32 v91, v2
	v_mov_b32_e32 v92, v2
	v_mov_b32_e32 v93, v2
	v_mov_b32_e32 v98, v2
	v_mov_b32_e32 v99, v2
	v_mov_b32_e32 v100, v2
	v_mov_b32_e32 v101, v2
	v_mov_b32_e32 v106, v2
	v_mov_b32_e32 v107, v2
	v_mov_b32_e32 v108, v2
	v_mov_b32_e32 v109, v2
	v_mov_b32_e32 v114, v2
	v_mov_b32_e32 v115, v2
	v_mov_b32_e32 v116, v2
	v_mov_b32_e32 v117, v2
	v_mov_b32_e32 v126, v2
	v_mov_b32_e32 v127, v2
	v_mov_b32_e32 v128, v2
	v_mov_b32_e32 v129, v2
	v_mov_b32_e32 v70, v2
	v_mov_b32_e32 v71, v2
	v_mov_b32_e32 v72, v2
	v_mov_b32_e32 v73, v2
	v_mov_b32_e32 v78, v2
	v_mov_b32_e32 v79, v2
	v_mov_b32_e32 v80, v2
	v_mov_b32_e32 v81, v2
	v_mov_b32_e32 v86, v2
	v_mov_b32_e32 v87, v2
	v_mov_b32_e32 v88, v2
	v_mov_b32_e32 v89, v2
	v_mov_b32_e32 v94, v2
	v_mov_b32_e32 v95, v2
	v_mov_b32_e32 v96, v2
	v_mov_b32_e32 v97, v2
	v_mov_b32_e32 v102, v2
	v_mov_b32_e32 v103, v2
	v_mov_b32_e32 v104, v2
	v_mov_b32_e32 v105, v2
	v_mov_b32_e32 v110, v2
	v_mov_b32_e32 v111, v2
	v_mov_b32_e32 v112, v2
	v_mov_b32_e32 v113, v2
	v_mov_b32_e32 v118, v2
	v_mov_b32_e32 v119, v2
	v_mov_b32_e32 v120, v2
	v_mov_b32_e32 v121, v2
	v_mov_b32_e32 v122, v2
	v_mov_b32_e32 v123, v2
	v_mov_b32_e32 v124, v2
	v_mov_b32_e32 v125, v2
